# up_proj epilogue: masked tap weights, halo zeroing and bf16 staging moves also packed (v_pk_mul_f32 / v_mov_b64), on top of the packed S2 loops
# speedup vs baseline: 1.0066x; 1.0066x over previous
.LBB0_1339:
	v_and_b32_e32 v56, 15, v0
	v_bfe_u32 v57, v0, 4, 2
	s_lshl_b32 s8, s12, 8
	s_add_i32 s8, s8, s63
	s_lshl_b32 s9, s13, 9
	s_lshl_b32 s22, s64, 2
	s_add_i32 s9, s9, s22
	v_lshl_add_u32 v235, v57, 5, s9
	global_load_dwordx4 v[100:103], v235, s[0:1]
	global_load_dwordx4 v[104:107], v235, s[30:31]
	global_load_dwordx4 v[112:115], v235, s[34:35]
	global_load_dwordx4 v[120:123], v235, s[2:3]
	global_load_dwordx4 v[92:95], v235, s[36:37]
	global_load_dwordx4 v[96:99], v235, s[48:49]
	global_load_dwordx4 v[108:111], v235, s[46:47]
	global_load_dwordx4 v[116:119], v235, s[44:45]
	v_cmp_lt_u32_e64 s[10:11], 13, v56
	v_cmp_gt_u32_e64 s[14:15], 2, v56
	v_cmp_eq_u32_e64 s[22:23], 0, v56
	v_lshlrev_b32_e32 v217, 8, v56
	v_lshl_add_u32 v217, v57, 5, v217
	v_add_u32_e32 v217, 0xfffff200, v217
	v_cndmask_b32_e64 v250, 0, 1.0, s[22:23]
	v_cndmask_b32_e64 v251, 0, 1.0, s[14:15]
	v_mul_u32_u24_e32 v234, 0x2c00, v56
	v_lshl_add_u32 v234, v57, 4, v234
	s_mov_b32 s41, 0xbfb8aa3b
	v_mov_b32_e32 v240, 0xbfb8aa3b
	v_mov_b32_e32 v241, 1.0
	s_lshl_b32 s39, s12, 8
	s_add_i32 s39, s39, s63
	s_mul_i32 s39, s39, 0x2c00
	s_lshl_b32 s40, s13, 8
	s_add_i32 s39, s39, s40
	s_lshl_b32 s40, s64, 1
	s_add_i32 s39, s39, s40
	s_add_u32 s16, s70, s39
	s_addc_u32 s17, s71, 0
	s_add_u32 s18, s16, 0x160000
	s_addc_u32 s19, s17, 0
	v_pk_mul_f32 v[192:193], v[192:193], v[242:243] op_sel_hi:[1,0]
	v_pk_mul_f32 v[194:195], v[194:195], v[242:243] op_sel_hi:[1,0]
	v_pk_mul_f32 v[160:161], v[160:161], v[242:243] op_sel_hi:[1,0]
	v_pk_mul_f32 v[162:163], v[162:163], v[242:243] op_sel_hi:[1,0]
	v_pk_mul_f32 v[180:181], v[180:181], v[242:243] op_sel_hi:[1,0]
	v_pk_mul_f32 v[182:183], v[182:183], v[242:243] op_sel_hi:[1,0]
	v_pk_mul_f32 v[156:157], v[156:157], v[242:243] op_sel_hi:[1,0]
	v_pk_mul_f32 v[158:159], v[158:159], v[242:243] op_sel_hi:[1,0]
	v_pk_mul_f32 v[188:189], v[188:189], v[242:243] op_sel:[0,1] op_sel_hi:[1,1]
	v_pk_mul_f32 v[190:191], v[190:191], v[242:243] op_sel:[0,1] op_sel_hi:[1,1]
	v_pk_mul_f32 v[152:153], v[152:153], v[242:243] op_sel:[0,1] op_sel_hi:[1,1]
	v_pk_mul_f32 v[154:155], v[154:155], v[242:243] op_sel:[0,1] op_sel_hi:[1,1]
	v_pk_mul_f32 v[184:185], v[184:185], v[242:243] op_sel:[0,1] op_sel_hi:[1,1]
	v_pk_mul_f32 v[186:187], v[186:187], v[242:243] op_sel:[0,1] op_sel_hi:[1,1]
	v_pk_mul_f32 v[148:149], v[148:149], v[242:243] op_sel:[0,1] op_sel_hi:[1,1]
	v_pk_mul_f32 v[150:151], v[150:151], v[242:243] op_sel:[0,1] op_sel_hi:[1,1]
	v_pk_mul_f32 v[176:177], v[176:177], v[244:245] op_sel_hi:[1,0]
	v_pk_mul_f32 v[178:179], v[178:179], v[244:245] op_sel_hi:[1,0]
	v_pk_mul_f32 v[144:145], v[144:145], v[244:245] op_sel_hi:[1,0]
	v_pk_mul_f32 v[146:147], v[146:147], v[244:245] op_sel_hi:[1,0]
	v_pk_mul_f32 v[172:173], v[172:173], v[244:245] op_sel_hi:[1,0]
	v_pk_mul_f32 v[174:175], v[174:175], v[244:245] op_sel_hi:[1,0]
	v_pk_mul_f32 v[140:141], v[140:141], v[244:245] op_sel_hi:[1,0]
	v_pk_mul_f32 v[142:143], v[142:143], v[244:245] op_sel_hi:[1,0]
	v_pk_mul_f32 v[168:169], v[168:169], v[244:245] op_sel:[0,1] op_sel_hi:[1,1]
	v_pk_mul_f32 v[170:171], v[170:171], v[244:245] op_sel:[0,1] op_sel_hi:[1,1]
	v_pk_mul_f32 v[136:137], v[136:137], v[244:245] op_sel:[0,1] op_sel_hi:[1,1]
	v_pk_mul_f32 v[138:139], v[138:139], v[244:245] op_sel:[0,1] op_sel_hi:[1,1]
	v_pk_mul_f32 v[164:165], v[164:165], v[244:245] op_sel:[0,1] op_sel_hi:[1,1]
	v_pk_mul_f32 v[166:167], v[166:167], v[244:245] op_sel:[0,1] op_sel_hi:[1,1]
	v_pk_mul_f32 v[132:133], v[132:133], v[244:245] op_sel:[0,1] op_sel_hi:[1,1]
	v_pk_mul_f32 v[134:135], v[134:135], v[244:245] op_sel:[0,1] op_sel_hi:[1,1]
	v_pk_mul_f32 v[128:129], v[128:129], v[246:247] op_sel_hi:[1,0]
	v_pk_mul_f32 v[130:131], v[130:131], v[246:247] op_sel_hi:[1,0]
	v_pk_mul_f32 v[64:65], v[64:65], v[246:247] op_sel_hi:[1,0]
	v_pk_mul_f32 v[66:67], v[66:67], v[246:247] op_sel_hi:[1,0]
	v_pk_mul_f32 v[124:125], v[124:125], v[246:247] op_sel_hi:[1,0]
	v_pk_mul_f32 v[126:127], v[126:127], v[246:247] op_sel_hi:[1,0]
	v_pk_mul_f32 v[60:61], v[60:61], v[246:247] op_sel_hi:[1,0]
	v_pk_mul_f32 v[62:63], v[62:63], v[246:247] op_sel_hi:[1,0]
	v_pk_mul_f32 v[88:89], v[88:89], v[246:247] op_sel:[0,1] op_sel_hi:[1,1]
	v_pk_mul_f32 v[90:91], v[90:91], v[246:247] op_sel:[0,1] op_sel_hi:[1,1]
	v_pk_mul_f32 v[24:25], v[24:25], v[246:247] op_sel:[0,1] op_sel_hi:[1,1]
	v_pk_mul_f32 v[26:27], v[26:27], v[246:247] op_sel:[0,1] op_sel_hi:[1,1]
	v_pk_mul_f32 v[84:85], v[84:85], v[246:247] op_sel:[0,1] op_sel_hi:[1,1]
	v_pk_mul_f32 v[86:87], v[86:87], v[246:247] op_sel:[0,1] op_sel_hi:[1,1]
	v_pk_mul_f32 v[20:21], v[20:21], v[246:247] op_sel:[0,1] op_sel_hi:[1,1]
	v_pk_mul_f32 v[22:23], v[22:23], v[246:247] op_sel:[0,1] op_sel_hi:[1,1]
	v_pk_mul_f32 v[80:81], v[80:81], v[248:249] op_sel_hi:[1,0]
	v_pk_mul_f32 v[82:83], v[82:83], v[248:249] op_sel_hi:[1,0]
	v_pk_mul_f32 v[16:17], v[16:17], v[248:249] op_sel_hi:[1,0]
	v_pk_mul_f32 v[18:19], v[18:19], v[248:249] op_sel_hi:[1,0]
	v_pk_mul_f32 v[76:77], v[76:77], v[248:249] op_sel_hi:[1,0]
	v_pk_mul_f32 v[78:79], v[78:79], v[248:249] op_sel_hi:[1,0]
	v_pk_mul_f32 v[12:13], v[12:13], v[248:249] op_sel_hi:[1,0]
	v_pk_mul_f32 v[14:15], v[14:15], v[248:249] op_sel_hi:[1,0]
	v_pk_mul_f32 v[72:73], v[72:73], v[248:249] op_sel:[0,1] op_sel_hi:[1,1]
	v_pk_mul_f32 v[74:75], v[74:75], v[248:249] op_sel:[0,1] op_sel_hi:[1,1]
	v_pk_mul_f32 v[8:9], v[8:9], v[248:249] op_sel:[0,1] op_sel_hi:[1,1]
	v_pk_mul_f32 v[10:11], v[10:11], v[248:249] op_sel:[0,1] op_sel_hi:[1,1]
	v_pk_mul_f32 v[68:69], v[68:69], v[248:249] op_sel:[0,1] op_sel_hi:[1,1]
	v_pk_mul_f32 v[70:71], v[70:71], v[248:249] op_sel:[0,1] op_sel_hi:[1,1]
	v_pk_mul_f32 v[4:5], v[4:5], v[248:249] op_sel:[0,1] op_sel_hi:[1,1]
	v_pk_mul_f32 v[6:7], v[6:7], v[248:249] op_sel:[0,1] op_sel_hi:[1,1]
	v_add_u32_e32 v58, s78, v217
	s_and_saveexec_b64 s[8:9], s[10:11]
	ds_write_b128 v58, v[168:171]
	ds_write_b128 v58, v[136:139] offset:16
	ds_write_b128 v58, v[164:167] offset:128
	ds_write_b128 v58, v[132:135] offset:144
	ds_write_b128 v58, v[72:75] offset:4096
	ds_write_b128 v58, v[8:11] offset:4112
	ds_write_b128 v58, v[68:71] offset:4224
	ds_write_b128 v58, v[4:7] offset:4240
	s_mov_b64 exec, s[8:9]
	s_waitcnt lgkmcnt(0)
	s_barrier
	s_waitcnt vmcnt(0)
	v_pk_mul_f32 v[28:29], v[104:105], v[250:251] op_sel_hi:[1,0]
	v_pk_mul_f32 v[30:31], v[106:107], v[250:251] op_sel_hi:[1,0]
	v_pk_mul_f32 v[32:33], v[100:101], v[250:251] op_sel:[0,1] op_sel_hi:[1,1]
	v_pk_mul_f32 v[34:35], v[102:103], v[250:251] op_sel:[0,1] op_sel_hi:[1,1]
	v_pk_mul_f32 v[36:37], v[96:97], v[250:251] op_sel_hi:[1,0]
	v_pk_mul_f32 v[38:39], v[98:99], v[250:251] op_sel_hi:[1,0]
	v_pk_mul_f32 v[40:41], v[92:93], v[250:251] op_sel:[0,1] op_sel_hi:[1,1]
	v_pk_mul_f32 v[42:43], v[94:95], v[250:251] op_sel:[0,1] op_sel_hi:[1,1]
	v_mov_b64_e32 v[196:197], 0
	v_mov_b64_e32 v[198:199], 0
	v_mov_b64_e32 v[200:201], 0
	v_mov_b64_e32 v[202:203], 0
	v_mov_b64_e32 v[204:205], 0
	v_mov_b64_e32 v[206:207], 0
	v_mov_b64_e32 v[208:209], 0
	v_mov_b64_e32 v[210:211], 0
	s_cmp_eq_u32 s63, 0
	s_cbranch_scc1 .Leu_pv0_skip_n0
	v_add_u32_e32 v58, s67, v217
	s_and_saveexec_b64 s[8:9], s[10:11]
	ds_read_b128 v[196:199], v58 offset:0
	ds_read_b128 v[200:203], v58 offset:128
	s_mov_b64 exec, s[8:9]

.Leu_halo_skip_a1n0:
	v_mov_b64_e32 v[196:197], 0
	v_mov_b64_e32 v[198:199], 0
	v_mov_b64_e32 v[200:201], 0
	v_mov_b64_e32 v[202:203], 0
	v_mov_b64_e32 v[204:205], 0
	v_mov_b64_e32 v[206:207], 0
	v_mov_b64_e32 v[208:209], 0
	v_mov_b64_e32 v[210:211], 0
	s_cmp_eq_u32 s63, 0
	s_cbranch_scc1 .Leu_pv0_skip_n1
	v_add_u32_e32 v58, s67, v217
	s_and_saveexec_b64 s[8:9], s[10:11]
	ds_read_b128 v[196:199], v58 offset:16
	ds_read_b128 v[200:203], v58 offset:144
	s_mov_b64 exec, s[8:9]
.Leu_pv0_skip_n1:
	s_cmp_eq_u32 s63, 0
	s_movk_i32 s40, 0x1000
	s_cselect_b32 s39, 0x800, s40
	s_add_i32 s39, s39, s67
	v_add_u32_e32 v59, s39, v217
	s_and_saveexec_b64 s[8:9], s[10:11]
	ds_read_b128 v[204:207], v59 offset:16
	ds_read_b128 v[208:211], v59 offset:144
	s_mov_b64 exec, s[8:9]
	s_waitcnt vmcnt(0) lgkmcnt(0)
	v_pk_mul_f32 v[28:29], v[192:193], v[250:251] op_sel_hi:[1,0]
	v_pk_mul_f32 v[30:31], v[194:195], v[250:251] op_sel_hi:[1,0]
	v_pk_mul_f32 v[32:33], v[236:237], v[250:251] op_sel:[0,1] op_sel_hi:[1,1]
	v_pk_mul_f32 v[34:35], v[238:239], v[250:251] op_sel:[0,1] op_sel_hi:[1,1]
	v_pk_mul_f32 v[36:37], v[176:177], v[250:251] op_sel_hi:[1,0]
	v_pk_mul_f32 v[38:39], v[178:179], v[250:251] op_sel_hi:[1,0]
	v_pk_mul_f32 v[40:41], v[184:185], v[250:251] op_sel:[0,1] op_sel_hi:[1,1]
	v_pk_mul_f32 v[42:43], v[186:187], v[250:251] op_sel:[0,1] op_sel_hi:[1,1]
	v_pk_fma_f32 v[44:45], v[180:181], v[160:161], v[188:189]
	v_pk_fma_f32 v[46:47], v[182:183], v[162:163], v[190:191]
	v_pk_fma_f32 v[48:49], v[172:173], v[156:157], v[168:169]
	v_pk_fma_f32 v[50:51], v[174:175], v[158:159], v[170:171]
	v_fmac_f32_dpp v44, v160, v192 row_shr:1 row_mask:0xf bank_mask:0xf
	v_fmac_f32_dpp v45, v161, v193 row_shr:1 row_mask:0xf bank_mask:0xf
	v_fmac_f32_dpp v46, v162, v194 row_shr:1 row_mask:0xf bank_mask:0xf
	v_fmac_f32_dpp v47, v163, v195 row_shr:1 row_mask:0xf bank_mask:0xf
	v_fmac_f32_dpp v48, v156, v176 row_shr:1 row_mask:0xf bank_mask:0xf
	v_fmac_f32_dpp v49, v157, v177 row_shr:1 row_mask:0xf bank_mask:0xf
	v_fmac_f32_dpp v50, v158, v178 row_shr:1 row_mask:0xf bank_mask:0xf
	v_fmac_f32_dpp v51, v159, v179 row_shr:1 row_mask:0xf bank_mask:0xf
	v_fmac_f32_dpp v44, v160, v236 row_shr:2 row_mask:0xf bank_mask:0xf
	v_fmac_f32_dpp v45, v161, v237 row_shr:2 row_mask:0xf bank_mask:0xf
	v_fmac_f32_dpp v46, v162, v238 row_shr:2 row_mask:0xf bank_mask:0xf
	v_fmac_f32_dpp v47, v163, v239 row_shr:2 row_mask:0xf bank_mask:0xf
	v_fmac_f32_dpp v48, v156, v184 row_shr:2 row_mask:0xf bank_mask:0xf
	v_fmac_f32_dpp v49, v157, v185 row_shr:2 row_mask:0xf bank_mask:0xf
	v_fmac_f32_dpp v50, v158, v186 row_shr:2 row_mask:0xf bank_mask:0xf
	v_fmac_f32_dpp v51, v159, v187 row_shr:2 row_mask:0xf bank_mask:0xf
	v_fmac_f32_dpp v44, v196, v28 row_ror:1 row_mask:0xf bank_mask:0xf
	v_fmac_f32_dpp v45, v197, v29 row_ror:1 row_mask:0xf bank_mask:0xf
	v_fmac_f32_dpp v46, v198, v30 row_ror:1 row_mask:0xf bank_mask:0xf
	v_fmac_f32_dpp v47, v199, v31 row_ror:1 row_mask:0xf bank_mask:0xf
	v_fmac_f32_dpp v48, v200, v36 row_ror:1 row_mask:0xf bank_mask:0xf
	v_fmac_f32_dpp v49, v201, v37 row_ror:1 row_mask:0xf bank_mask:0xf
	v_fmac_f32_dpp v50, v202, v38 row_ror:1 row_mask:0xf bank_mask:0xf
	v_fmac_f32_dpp v51, v203, v39 row_ror:1 row_mask:0xf bank_mask:0xf
	v_fmac_f32_dpp v44, v196, v32 row_ror:2 row_mask:0xf bank_mask:0xf
	v_fmac_f32_dpp v45, v197, v33 row_ror:2 row_mask:0xf bank_mask:0xf
	v_fmac_f32_dpp v46, v198, v34 row_ror:2 row_mask:0xf bank_mask:0xf
	v_fmac_f32_dpp v47, v199, v35 row_ror:2 row_mask:0xf bank_mask:0xf
	v_fmac_f32_dpp v48, v200, v40 row_ror:2 row_mask:0xf bank_mask:0xf
	v_fmac_f32_dpp v49, v201, v41 row_ror:2 row_mask:0xf bank_mask:0xf
	v_fmac_f32_dpp v50, v202, v42 row_ror:2 row_mask:0xf bank_mask:0xf
	v_fmac_f32_dpp v51, v203, v43 row_ror:2 row_mask:0xf bank_mask:0xf
	v_pk_mul_f32 v[52:53], v[44:45], v[240:241] op_sel_hi:[1,0]
	v_pk_mul_f32 v[54:55], v[46:47], v[240:241] op_sel_hi:[1,0]
	v_exp_f32_e32 v52, v52
	v_exp_f32_e32 v53, v53
	v_exp_f32_e32 v54, v54
	v_exp_f32_e32 v55, v55
	v_pk_add_f32 v[52:53], v[52:53], v[240:241] op_sel:[0,1] op_sel_hi:[1,1]
	v_pk_add_f32 v[54:55], v[54:55], v[240:241] op_sel:[0,1] op_sel_hi:[1,1]
	v_rcp_f32_e32 v52, v52
	v_rcp_f32_e32 v53, v53
	v_rcp_f32_e32 v54, v54
	v_rcp_f32_e32 v55, v55
	v_pk_mul_f32 v[44:45], v[44:45], v[52:53]
	v_pk_mul_f32 v[46:47], v[46:47], v[54:55]
	v_pk_mul_f32 v[44:45], v[48:49], v[44:45]
	v_pk_mul_f32 v[46:47], v[50:51], v[46:47]
	v_mov_b64_e32 v[124:125], v[242:243]
	v_cvt_pk_bf16_f32 v126, v44, v45
	v_cvt_pk_bf16_f32 v127, v46, v47
	v_mov_b32_e32 v58, v234
	s_mov_b64 s[8:9], exec
	s_and_b32 s39, s12, 7
	s_cmp_eq_u32 s39, 0
	s_cbranch_scc1 .Leu_g00_all
	s_cmp_lg_u32 s63, 0
	s_cbranch_scc1 .Leu_g00_all
	s_andn2_b64 exec, exec, s[14:15]

.Leu_halo_skip_a0n1:
	v_pk_fma_f32 v[44:45], v[180:181], v[152:153], v[188:189]
	v_pk_fma_f32 v[46:47], v[182:183], v[154:155], v[190:191]
	v_pk_fma_f32 v[48:49], v[172:173], v[148:149], v[168:169]
	v_pk_fma_f32 v[50:51], v[174:175], v[150:151], v[170:171]
	v_fmac_f32_dpp v44, v152, v192 row_shr:1 row_mask:0xf bank_mask:0xf
	v_fmac_f32_dpp v45, v153, v193 row_shr:1 row_mask:0xf bank_mask:0xf
	v_fmac_f32_dpp v46, v154, v194 row_shr:1 row_mask:0xf bank_mask:0xf
	v_fmac_f32_dpp v47, v155, v195 row_shr:1 row_mask:0xf bank_mask:0xf
	v_fmac_f32_dpp v48, v148, v176 row_shr:1 row_mask:0xf bank_mask:0xf
	v_fmac_f32_dpp v49, v149, v177 row_shr:1 row_mask:0xf bank_mask:0xf
	v_fmac_f32_dpp v50, v150, v178 row_shr:1 row_mask:0xf bank_mask:0xf
	v_fmac_f32_dpp v51, v151, v179 row_shr:1 row_mask:0xf bank_mask:0xf
	v_fmac_f32_dpp v44, v152, v236 row_shr:2 row_mask:0xf bank_mask:0xf
	v_fmac_f32_dpp v45, v153, v237 row_shr:2 row_mask:0xf bank_mask:0xf
	v_fmac_f32_dpp v46, v154, v238 row_shr:2 row_mask:0xf bank_mask:0xf
	v_fmac_f32_dpp v47, v155, v239 row_shr:2 row_mask:0xf bank_mask:0xf
	v_fmac_f32_dpp v48, v148, v184 row_shr:2 row_mask:0xf bank_mask:0xf
	v_fmac_f32_dpp v49, v149, v185 row_shr:2 row_mask:0xf bank_mask:0xf
	v_fmac_f32_dpp v50, v150, v186 row_shr:2 row_mask:0xf bank_mask:0xf
	v_fmac_f32_dpp v51, v151, v187 row_shr:2 row_mask:0xf bank_mask:0xf
	v_fmac_f32_dpp v44, v160, v28 row_ror:1 row_mask:0xf bank_mask:0xf
	v_fmac_f32_dpp v45, v161, v29 row_ror:1 row_mask:0xf bank_mask:0xf
	v_fmac_f32_dpp v46, v162, v30 row_ror:1 row_mask:0xf bank_mask:0xf
	v_fmac_f32_dpp v47, v163, v31 row_ror:1 row_mask:0xf bank_mask:0xf
	v_fmac_f32_dpp v48, v156, v36 row_ror:1 row_mask:0xf bank_mask:0xf
	v_fmac_f32_dpp v49, v157, v37 row_ror:1 row_mask:0xf bank_mask:0xf
	v_fmac_f32_dpp v50, v158, v38 row_ror:1 row_mask:0xf bank_mask:0xf
	v_fmac_f32_dpp v51, v159, v39 row_ror:1 row_mask:0xf bank_mask:0xf
	v_fmac_f32_dpp v44, v160, v32 row_ror:2 row_mask:0xf bank_mask:0xf
	v_fmac_f32_dpp v45, v161, v33 row_ror:2 row_mask:0xf bank_mask:0xf
	v_fmac_f32_dpp v46, v162, v34 row_ror:2 row_mask:0xf bank_mask:0xf
	v_fmac_f32_dpp v47, v163, v35 row_ror:2 row_mask:0xf bank_mask:0xf
	v_fmac_f32_dpp v48, v156, v40 row_ror:2 row_mask:0xf bank_mask:0xf
	v_fmac_f32_dpp v49, v157, v41 row_ror:2 row_mask:0xf bank_mask:0xf
	v_fmac_f32_dpp v50, v158, v42 row_ror:2 row_mask:0xf bank_mask:0xf
	v_fmac_f32_dpp v51, v159, v43 row_ror:2 row_mask:0xf bank_mask:0xf
	v_pk_mul_f32 v[52:53], v[44:45], v[240:241] op_sel_hi:[1,0]
	v_pk_mul_f32 v[54:55], v[46:47], v[240:241] op_sel_hi:[1,0]
	v_exp_f32_e32 v52, v52
	v_exp_f32_e32 v53, v53
	v_exp_f32_e32 v54, v54
	v_exp_f32_e32 v55, v55
	v_pk_add_f32 v[52:53], v[52:53], v[240:241] op_sel:[0,1] op_sel_hi:[1,1]
	v_pk_add_f32 v[54:55], v[54:55], v[240:241] op_sel:[0,1] op_sel_hi:[1,1]
	v_rcp_f32_e32 v52, v52
	v_rcp_f32_e32 v53, v53
	v_rcp_f32_e32 v54, v54
	v_rcp_f32_e32 v55, v55
	v_pk_mul_f32 v[44:45], v[44:45], v[52:53]
	v_pk_mul_f32 v[46:47], v[46:47], v[54:55]
	v_pk_mul_f32 v[44:45], v[48:49], v[44:45]
	v_pk_mul_f32 v[46:47], v[50:51], v[46:47]
	v_mov_b64_e32 v[88:89], v[244:245]
	v_cvt_pk_bf16_f32 v90, v44, v45
	v_cvt_pk_bf16_f32 v91, v46, v47
	v_add_u32_e32 v58, 0x2c000, v234
	global_store_dwordx4 v58, v[88:91], s[16:17]
	v_pk_fma_f32 v[44:45], v[180:181], v[144:145], v[188:189]
	v_pk_fma_f32 v[46:47], v[182:183], v[146:147], v[190:191]
	v_pk_fma_f32 v[48:49], v[172:173], v[140:141], v[168:169]
	v_pk_fma_f32 v[50:51], v[174:175], v[142:143], v[170:171]
	v_fmac_f32_dpp v44, v144, v192 row_shr:1 row_mask:0xf bank_mask:0xf
	v_fmac_f32_dpp v45, v145, v193 row_shr:1 row_mask:0xf bank_mask:0xf
	v_fmac_f32_dpp v46, v146, v194 row_shr:1 row_mask:0xf bank_mask:0xf
	v_fmac_f32_dpp v47, v147, v195 row_shr:1 row_mask:0xf bank_mask:0xf
	v_fmac_f32_dpp v48, v140, v176 row_shr:1 row_mask:0xf bank_mask:0xf
	v_fmac_f32_dpp v49, v141, v177 row_shr:1 row_mask:0xf bank_mask:0xf
	v_fmac_f32_dpp v50, v142, v178 row_shr:1 row_mask:0xf bank_mask:0xf
	v_fmac_f32_dpp v51, v143, v179 row_shr:1 row_mask:0xf bank_mask:0xf
	v_fmac_f32_dpp v44, v144, v236 row_shr:2 row_mask:0xf bank_mask:0xf
	v_fmac_f32_dpp v45, v145, v237 row_shr:2 row_mask:0xf bank_mask:0xf
	v_fmac_f32_dpp v46, v146, v238 row_shr:2 row_mask:0xf bank_mask:0xf
	v_fmac_f32_dpp v47, v147, v239 row_shr:2 row_mask:0xf bank_mask:0xf
	v_fmac_f32_dpp v48, v140, v184 row_shr:2 row_mask:0xf bank_mask:0xf
	v_fmac_f32_dpp v49, v141, v185 row_shr:2 row_mask:0xf bank_mask:0xf
	v_fmac_f32_dpp v50, v142, v186 row_shr:2 row_mask:0xf bank_mask:0xf
	v_fmac_f32_dpp v51, v143, v187 row_shr:2 row_mask:0xf bank_mask:0xf
	v_fmac_f32_dpp v44, v152, v28 row_ror:1 row_mask:0xf bank_mask:0xf
	v_fmac_f32_dpp v45, v153, v29 row_ror:1 row_mask:0xf bank_mask:0xf
	v_fmac_f32_dpp v46, v154, v30 row_ror:1 row_mask:0xf bank_mask:0xf
	v_fmac_f32_dpp v47, v155, v31 row_ror:1 row_mask:0xf bank_mask:0xf
	v_fmac_f32_dpp v48, v148, v36 row_ror:1 row_mask:0xf bank_mask:0xf
	v_fmac_f32_dpp v49, v149, v37 row_ror:1 row_mask:0xf bank_mask:0xf
	v_fmac_f32_dpp v50, v150, v38 row_ror:1 row_mask:0xf bank_mask:0xf
	v_fmac_f32_dpp v51, v151, v39 row_ror:1 row_mask:0xf bank_mask:0xf
	v_fmac_f32_dpp v44, v152, v32 row_ror:2 row_mask:0xf bank_mask:0xf
	v_fmac_f32_dpp v45, v153, v33 row_ror:2 row_mask:0xf bank_mask:0xf
	v_fmac_f32_dpp v46, v154, v34 row_ror:2 row_mask:0xf bank_mask:0xf
	v_fmac_f32_dpp v47, v155, v35 row_ror:2 row_mask:0xf bank_mask:0xf
	v_fmac_f32_dpp v48, v148, v40 row_ror:2 row_mask:0xf bank_mask:0xf
	v_fmac_f32_dpp v49, v149, v41 row_ror:2 row_mask:0xf bank_mask:0xf
	v_fmac_f32_dpp v50, v150, v42 row_ror:2 row_mask:0xf bank_mask:0xf
	v_fmac_f32_dpp v51, v151, v43 row_ror:2 row_mask:0xf bank_mask:0xf
	v_pk_mul_f32 v[52:53], v[44:45], v[240:241] op_sel_hi:[1,0]
	v_pk_mul_f32 v[54:55], v[46:47], v[240:241] op_sel_hi:[1,0]
	v_exp_f32_e32 v52, v52
	v_exp_f32_e32 v53, v53
	v_exp_f32_e32 v54, v54
	v_exp_f32_e32 v55, v55
	v_pk_add_f32 v[52:53], v[52:53], v[240:241] op_sel:[0,1] op_sel_hi:[1,1]
	v_pk_add_f32 v[54:55], v[54:55], v[240:241] op_sel:[0,1] op_sel_hi:[1,1]
	v_rcp_f32_e32 v52, v52
	v_rcp_f32_e32 v53, v53
	v_rcp_f32_e32 v54, v54
	v_rcp_f32_e32 v55, v55
	v_pk_mul_f32 v[44:45], v[44:45], v[52:53]
	v_pk_mul_f32 v[46:47], v[46:47], v[54:55]
	v_pk_mul_f32 v[44:45], v[48:49], v[44:45]
	v_pk_mul_f32 v[46:47], v[50:51], v[46:47]
	v_mov_b64_e32 v[124:125], v[246:247]
	v_cvt_pk_bf16_f32 v126, v44, v45
	v_cvt_pk_bf16_f32 v127, v46, v47
	v_add_u32_e32 v58, 0x58000, v234
	global_store_dwordx4 v58, v[124:127], s[16:17]
	v_pk_fma_f32 v[44:45], v[180:181], v[136:137], v[188:189]
	v_pk_fma_f32 v[46:47], v[182:183], v[138:139], v[190:191]
	v_pk_fma_f32 v[48:49], v[172:173], v[132:133], v[168:169]
	v_pk_fma_f32 v[50:51], v[174:175], v[134:135], v[170:171]
	v_fmac_f32_dpp v44, v136, v192 row_shr:1 row_mask:0xf bank_mask:0xf
	v_fmac_f32_dpp v45, v137, v193 row_shr:1 row_mask:0xf bank_mask:0xf
	v_fmac_f32_dpp v46, v138, v194 row_shr:1 row_mask:0xf bank_mask:0xf
	v_fmac_f32_dpp v47, v139, v195 row_shr:1 row_mask:0xf bank_mask:0xf
	v_fmac_f32_dpp v48, v132, v176 row_shr:1 row_mask:0xf bank_mask:0xf
	v_fmac_f32_dpp v49, v133, v177 row_shr:1 row_mask:0xf bank_mask:0xf
	v_fmac_f32_dpp v50, v134, v178 row_shr:1 row_mask:0xf bank_mask:0xf
	v_fmac_f32_dpp v51, v135, v179 row_shr:1 row_mask:0xf bank_mask:0xf
	v_fmac_f32_dpp v44, v136, v236 row_shr:2 row_mask:0xf bank_mask:0xf
	v_fmac_f32_dpp v45, v137, v237 row_shr:2 row_mask:0xf bank_mask:0xf
	v_fmac_f32_dpp v46, v138, v238 row_shr:2 row_mask:0xf bank_mask:0xf
	v_fmac_f32_dpp v47, v139, v239 row_shr:2 row_mask:0xf bank_mask:0xf
	v_fmac_f32_dpp v48, v132, v184 row_shr:2 row_mask:0xf bank_mask:0xf
	v_fmac_f32_dpp v49, v133, v185 row_shr:2 row_mask:0xf bank_mask:0xf
	v_fmac_f32_dpp v50, v134, v186 row_shr:2 row_mask:0xf bank_mask:0xf
	v_fmac_f32_dpp v51, v135, v187 row_shr:2 row_mask:0xf bank_mask:0xf
	v_fmac_f32_dpp v44, v144, v28 row_ror:1 row_mask:0xf bank_mask:0xf
	v_fmac_f32_dpp v45, v145, v29 row_ror:1 row_mask:0xf bank_mask:0xf
	v_fmac_f32_dpp v46, v146, v30 row_ror:1 row_mask:0xf bank_mask:0xf
	v_fmac_f32_dpp v47, v147, v31 row_ror:1 row_mask:0xf bank_mask:0xf
	v_fmac_f32_dpp v48, v140, v36 row_ror:1 row_mask:0xf bank_mask:0xf
	v_fmac_f32_dpp v49, v141, v37 row_ror:1 row_mask:0xf bank_mask:0xf
	v_fmac_f32_dpp v50, v142, v38 row_ror:1 row_mask:0xf bank_mask:0xf
	v_fmac_f32_dpp v51, v143, v39 row_ror:1 row_mask:0xf bank_mask:0xf
	v_fmac_f32_dpp v44, v144, v32 row_ror:2 row_mask:0xf bank_mask:0xf
	v_fmac_f32_dpp v45, v145, v33 row_ror:2 row_mask:0xf bank_mask:0xf
	v_fmac_f32_dpp v46, v146, v34 row_ror:2 row_mask:0xf bank_mask:0xf
	v_fmac_f32_dpp v47, v147, v35 row_ror:2 row_mask:0xf bank_mask:0xf
	v_fmac_f32_dpp v48, v140, v40 row_ror:2 row_mask:0xf bank_mask:0xf
	v_fmac_f32_dpp v49, v141, v41 row_ror:2 row_mask:0xf bank_mask:0xf
	v_fmac_f32_dpp v50, v142, v42 row_ror:2 row_mask:0xf bank_mask:0xf
	v_fmac_f32_dpp v51, v143, v43 row_ror:2 row_mask:0xf bank_mask:0xf
	v_pk_mul_f32 v[52:53], v[44:45], v[240:241] op_sel_hi:[1,0]
	v_pk_mul_f32 v[54:55], v[46:47], v[240:241] op_sel_hi:[1,0]
	v_exp_f32_e32 v52, v52
	v_exp_f32_e32 v53, v53
	v_exp_f32_e32 v54, v54
	v_exp_f32_e32 v55, v55
	v_pk_add_f32 v[52:53], v[52:53], v[240:241] op_sel:[0,1] op_sel_hi:[1,1]
	v_pk_add_f32 v[54:55], v[54:55], v[240:241] op_sel:[0,1] op_sel_hi:[1,1]
	v_rcp_f32_e32 v52, v52
	v_rcp_f32_e32 v53, v53
	v_rcp_f32_e32 v54, v54
	v_rcp_f32_e32 v55, v55
	v_pk_mul_f32 v[44:45], v[44:45], v[52:53]
	v_pk_mul_f32 v[46:47], v[46:47], v[54:55]
	v_pk_mul_f32 v[44:45], v[48:49], v[44:45]
	v_pk_mul_f32 v[46:47], v[50:51], v[46:47]
	v_mov_b64_e32 v[88:89], v[248:249]
	v_cvt_pk_bf16_f32 v90, v44, v45
	v_cvt_pk_bf16_f32 v91, v46, v47
	v_add_u32_e32 v58, 0x84000, v234
	global_store_dwordx4 v58, v[88:91], s[16:17]
	v_pk_fma_f32 v[44:45], v[180:181], v[64:65], v[188:189]
	v_pk_fma_f32 v[46:47], v[182:183], v[66:67], v[190:191]
	v_pk_fma_f32 v[48:49], v[172:173], v[60:61], v[168:169]
	v_pk_fma_f32 v[50:51], v[174:175], v[62:63], v[170:171]
	v_fmac_f32_dpp v44, v64, v192 row_shr:1 row_mask:0xf bank_mask:0xf
	v_fmac_f32_dpp v45, v65, v193 row_shr:1 row_mask:0xf bank_mask:0xf
	v_fmac_f32_dpp v46, v66, v194 row_shr:1 row_mask:0xf bank_mask:0xf
	v_fmac_f32_dpp v47, v67, v195 row_shr:1 row_mask:0xf bank_mask:0xf
	v_fmac_f32_dpp v48, v60, v176 row_shr:1 row_mask:0xf bank_mask:0xf
	v_fmac_f32_dpp v49, v61, v177 row_shr:1 row_mask:0xf bank_mask:0xf
	v_fmac_f32_dpp v50, v62, v178 row_shr:1 row_mask:0xf bank_mask:0xf
	v_fmac_f32_dpp v51, v63, v179 row_shr:1 row_mask:0xf bank_mask:0xf
	v_fmac_f32_dpp v44, v64, v236 row_shr:2 row_mask:0xf bank_mask:0xf
	v_fmac_f32_dpp v45, v65, v237 row_shr:2 row_mask:0xf bank_mask:0xf
	v_fmac_f32_dpp v46, v66, v238 row_shr:2 row_mask:0xf bank_mask:0xf
	v_fmac_f32_dpp v47, v67, v239 row_shr:2 row_mask:0xf bank_mask:0xf
	v_fmac_f32_dpp v48, v60, v184 row_shr:2 row_mask:0xf bank_mask:0xf
	v_fmac_f32_dpp v49, v61, v185 row_shr:2 row_mask:0xf bank_mask:0xf
	v_fmac_f32_dpp v50, v62, v186 row_shr:2 row_mask:0xf bank_mask:0xf
	v_fmac_f32_dpp v51, v63, v187 row_shr:2 row_mask:0xf bank_mask:0xf
	v_fmac_f32_dpp v44, v204, v28 row_ror:1 row_mask:0xf bank_mask:0xf
	v_fmac_f32_dpp v45, v205, v29 row_ror:1 row_mask:0xf bank_mask:0xf
	v_fmac_f32_dpp v46, v206, v30 row_ror:1 row_mask:0xf bank_mask:0xf
	v_fmac_f32_dpp v47, v207, v31 row_ror:1 row_mask:0xf bank_mask:0xf
	v_fmac_f32_dpp v48, v208, v36 row_ror:1 row_mask:0xf bank_mask:0xf
	v_fmac_f32_dpp v49, v209, v37 row_ror:1 row_mask:0xf bank_mask:0xf
	v_fmac_f32_dpp v50, v210, v38 row_ror:1 row_mask:0xf bank_mask:0xf
	v_fmac_f32_dpp v51, v211, v39 row_ror:1 row_mask:0xf bank_mask:0xf
	v_fmac_f32_dpp v44, v204, v32 row_ror:2 row_mask:0xf bank_mask:0xf
	v_fmac_f32_dpp v45, v205, v33 row_ror:2 row_mask:0xf bank_mask:0xf
	v_fmac_f32_dpp v46, v206, v34 row_ror:2 row_mask:0xf bank_mask:0xf
	v_fmac_f32_dpp v47, v207, v35 row_ror:2 row_mask:0xf bank_mask:0xf
	v_fmac_f32_dpp v48, v208, v40 row_ror:2 row_mask:0xf bank_mask:0xf
	v_fmac_f32_dpp v49, v209, v41 row_ror:2 row_mask:0xf bank_mask:0xf
	v_fmac_f32_dpp v50, v210, v42 row_ror:2 row_mask:0xf bank_mask:0xf
	v_fmac_f32_dpp v51, v211, v43 row_ror:2 row_mask:0xf bank_mask:0xf
	v_pk_mul_f32 v[52:53], v[44:45], v[240:241] op_sel_hi:[1,0]
	v_pk_mul_f32 v[54:55], v[46:47], v[240:241] op_sel_hi:[1,0]
	v_exp_f32_e32 v52, v52
	v_exp_f32_e32 v53, v53
	v_exp_f32_e32 v54, v54
	v_exp_f32_e32 v55, v55
	v_pk_add_f32 v[52:53], v[52:53], v[240:241] op_sel:[0,1] op_sel_hi:[1,1]
	v_pk_add_f32 v[54:55], v[54:55], v[240:241] op_sel:[0,1] op_sel_hi:[1,1]
	v_rcp_f32_e32 v52, v52
	v_rcp_f32_e32 v53, v53
	v_rcp_f32_e32 v54, v54
	v_rcp_f32_e32 v55, v55
	v_pk_mul_f32 v[44:45], v[44:45], v[52:53]
	v_pk_mul_f32 v[46:47], v[46:47], v[54:55]
	v_pk_mul_f32 v[44:45], v[48:49], v[44:45]
	v_pk_mul_f32 v[46:47], v[50:51], v[46:47]
	v_mov_b64_e32 v[124:125], v[164:165]
	v_cvt_pk_bf16_f32 v126, v44, v45
	v_cvt_pk_bf16_f32 v127, v46, v47
	v_mov_b32_e32 v58, v234
	global_store_dwordx4 v58, v[124:127], s[18:19]
	v_pk_fma_f32 v[44:45], v[180:181], v[24:25], v[188:189]
	v_pk_fma_f32 v[46:47], v[182:183], v[26:27], v[190:191]
	v_pk_fma_f32 v[48:49], v[172:173], v[20:21], v[168:169]
	v_pk_fma_f32 v[50:51], v[174:175], v[22:23], v[170:171]
	v_fmac_f32_dpp v44, v24, v192 row_shr:1 row_mask:0xf bank_mask:0xf
	v_fmac_f32_dpp v45, v25, v193 row_shr:1 row_mask:0xf bank_mask:0xf
	v_fmac_f32_dpp v46, v26, v194 row_shr:1 row_mask:0xf bank_mask:0xf
	v_fmac_f32_dpp v47, v27, v195 row_shr:1 row_mask:0xf bank_mask:0xf
	v_fmac_f32_dpp v48, v20, v176 row_shr:1 row_mask:0xf bank_mask:0xf
	v_fmac_f32_dpp v49, v21, v177 row_shr:1 row_mask:0xf bank_mask:0xf
	v_fmac_f32_dpp v50, v22, v178 row_shr:1 row_mask:0xf bank_mask:0xf
	v_fmac_f32_dpp v51, v23, v179 row_shr:1 row_mask:0xf bank_mask:0xf
	v_fmac_f32_dpp v44, v24, v236 row_shr:2 row_mask:0xf bank_mask:0xf
	v_fmac_f32_dpp v45, v25, v237 row_shr:2 row_mask:0xf bank_mask:0xf
	v_fmac_f32_dpp v46, v26, v238 row_shr:2 row_mask:0xf bank_mask:0xf
	v_fmac_f32_dpp v47, v27, v239 row_shr:2 row_mask:0xf bank_mask:0xf
	v_fmac_f32_dpp v48, v20, v184 row_shr:2 row_mask:0xf bank_mask:0xf
	v_fmac_f32_dpp v49, v21, v185 row_shr:2 row_mask:0xf bank_mask:0xf
	v_fmac_f32_dpp v50, v22, v186 row_shr:2 row_mask:0xf bank_mask:0xf
	v_fmac_f32_dpp v51, v23, v187 row_shr:2 row_mask:0xf bank_mask:0xf
	v_fmac_f32_dpp v44, v64, v28 row_ror:1 row_mask:0xf bank_mask:0xf
	v_fmac_f32_dpp v45, v65, v29 row_ror:1 row_mask:0xf bank_mask:0xf
	v_fmac_f32_dpp v46, v66, v30 row_ror:1 row_mask:0xf bank_mask:0xf
	v_fmac_f32_dpp v47, v67, v31 row_ror:1 row_mask:0xf bank_mask:0xf
	v_fmac_f32_dpp v48, v60, v36 row_ror:1 row_mask:0xf bank_mask:0xf
	v_fmac_f32_dpp v49, v61, v37 row_ror:1 row_mask:0xf bank_mask:0xf
	v_fmac_f32_dpp v50, v62, v38 row_ror:1 row_mask:0xf bank_mask:0xf
	v_fmac_f32_dpp v51, v63, v39 row_ror:1 row_mask:0xf bank_mask:0xf
	v_fmac_f32_dpp v44, v64, v32 row_ror:2 row_mask:0xf bank_mask:0xf
	v_fmac_f32_dpp v45, v65, v33 row_ror:2 row_mask:0xf bank_mask:0xf
	v_fmac_f32_dpp v46, v66, v34 row_ror:2 row_mask:0xf bank_mask:0xf
	v_fmac_f32_dpp v47, v67, v35 row_ror:2 row_mask:0xf bank_mask:0xf
	v_fmac_f32_dpp v48, v60, v40 row_ror:2 row_mask:0xf bank_mask:0xf
	v_fmac_f32_dpp v49, v61, v41 row_ror:2 row_mask:0xf bank_mask:0xf
	v_fmac_f32_dpp v50, v62, v42 row_ror:2 row_mask:0xf bank_mask:0xf
	v_fmac_f32_dpp v51, v63, v43 row_ror:2 row_mask:0xf bank_mask:0xf
	v_pk_mul_f32 v[52:53], v[44:45], v[240:241] op_sel_hi:[1,0]
	v_pk_mul_f32 v[54:55], v[46:47], v[240:241] op_sel_hi:[1,0]
	v_exp_f32_e32 v52, v52
	v_exp_f32_e32 v53, v53
	v_exp_f32_e32 v54, v54
	v_exp_f32_e32 v55, v55
	v_pk_add_f32 v[52:53], v[52:53], v[240:241] op_sel:[0,1] op_sel_hi:[1,1]
	v_pk_add_f32 v[54:55], v[54:55], v[240:241] op_sel:[0,1] op_sel_hi:[1,1]
	v_rcp_f32_e32 v52, v52
	v_rcp_f32_e32 v53, v53
	v_rcp_f32_e32 v54, v54
	v_rcp_f32_e32 v55, v55
	v_pk_mul_f32 v[44:45], v[44:45], v[52:53]
	v_pk_mul_f32 v[46:47], v[46:47], v[54:55]
	v_pk_mul_f32 v[44:45], v[48:49], v[44:45]
	v_pk_mul_f32 v[46:47], v[50:51], v[46:47]
	v_mov_b64_e32 v[88:89], v[166:167]
	v_cvt_pk_bf16_f32 v90, v44, v45
	v_cvt_pk_bf16_f32 v91, v46, v47
	v_add_u32_e32 v58, 0x2c000, v234
	global_store_dwordx4 v58, v[88:91], s[18:19]
	v_pk_fma_f32 v[44:45], v[180:181], v[16:17], v[188:189]
	v_pk_fma_f32 v[46:47], v[182:183], v[18:19], v[190:191]
	v_pk_fma_f32 v[48:49], v[172:173], v[12:13], v[168:169]
	v_pk_fma_f32 v[50:51], v[174:175], v[14:15], v[170:171]
	v_fmac_f32_dpp v44, v16, v192 row_shr:1 row_mask:0xf bank_mask:0xf
	v_fmac_f32_dpp v45, v17, v193 row_shr:1 row_mask:0xf bank_mask:0xf
	v_fmac_f32_dpp v46, v18, v194 row_shr:1 row_mask:0xf bank_mask:0xf
	v_fmac_f32_dpp v47, v19, v195 row_shr:1 row_mask:0xf bank_mask:0xf
	v_fmac_f32_dpp v48, v12, v176 row_shr:1 row_mask:0xf bank_mask:0xf
	v_fmac_f32_dpp v49, v13, v177 row_shr:1 row_mask:0xf bank_mask:0xf
	v_fmac_f32_dpp v50, v14, v178 row_shr:1 row_mask:0xf bank_mask:0xf
	v_fmac_f32_dpp v51, v15, v179 row_shr:1 row_mask:0xf bank_mask:0xf
	v_fmac_f32_dpp v44, v16, v236 row_shr:2 row_mask:0xf bank_mask:0xf
	v_fmac_f32_dpp v45, v17, v237 row_shr:2 row_mask:0xf bank_mask:0xf
	v_fmac_f32_dpp v46, v18, v238 row_shr:2 row_mask:0xf bank_mask:0xf
	v_fmac_f32_dpp v47, v19, v239 row_shr:2 row_mask:0xf bank_mask:0xf
	v_fmac_f32_dpp v48, v12, v184 row_shr:2 row_mask:0xf bank_mask:0xf
	v_fmac_f32_dpp v49, v13, v185 row_shr:2 row_mask:0xf bank_mask:0xf
	v_fmac_f32_dpp v50, v14, v186 row_shr:2 row_mask:0xf bank_mask:0xf
	v_fmac_f32_dpp v51, v15, v187 row_shr:2 row_mask:0xf bank_mask:0xf
	v_fmac_f32_dpp v44, v24, v28 row_ror:1 row_mask:0xf bank_mask:0xf
	v_fmac_f32_dpp v45, v25, v29 row_ror:1 row_mask:0xf bank_mask:0xf
	v_fmac_f32_dpp v46, v26, v30 row_ror:1 row_mask:0xf bank_mask:0xf
	v_fmac_f32_dpp v47, v27, v31 row_ror:1 row_mask:0xf bank_mask:0xf
	v_fmac_f32_dpp v48, v20, v36 row_ror:1 row_mask:0xf bank_mask:0xf
	v_fmac_f32_dpp v49, v21, v37 row_ror:1 row_mask:0xf bank_mask:0xf
	v_fmac_f32_dpp v50, v22, v38 row_ror:1 row_mask:0xf bank_mask:0xf
	v_fmac_f32_dpp v51, v23, v39 row_ror:1 row_mask:0xf bank_mask:0xf
	v_fmac_f32_dpp v44, v24, v32 row_ror:2 row_mask:0xf bank_mask:0xf
	v_fmac_f32_dpp v45, v25, v33 row_ror:2 row_mask:0xf bank_mask:0xf
	v_fmac_f32_dpp v46, v26, v34 row_ror:2 row_mask:0xf bank_mask:0xf
	v_fmac_f32_dpp v47, v27, v35 row_ror:2 row_mask:0xf bank_mask:0xf
	v_fmac_f32_dpp v48, v20, v40 row_ror:2 row_mask:0xf bank_mask:0xf
	v_fmac_f32_dpp v49, v21, v41 row_ror:2 row_mask:0xf bank_mask:0xf
	v_fmac_f32_dpp v50, v22, v42 row_ror:2 row_mask:0xf bank_mask:0xf
	v_fmac_f32_dpp v51, v23, v43 row_ror:2 row_mask:0xf bank_mask:0xf
	v_pk_mul_f32 v[52:53], v[44:45], v[240:241] op_sel_hi:[1,0]
	v_pk_mul_f32 v[54:55], v[46:47], v[240:241] op_sel_hi:[1,0]
	v_exp_f32_e32 v52, v52
	v_exp_f32_e32 v53, v53
	v_exp_f32_e32 v54, v54
	v_exp_f32_e32 v55, v55
	v_pk_add_f32 v[52:53], v[52:53], v[240:241] op_sel:[0,1] op_sel_hi:[1,1]
	v_pk_add_f32 v[54:55], v[54:55], v[240:241] op_sel:[0,1] op_sel_hi:[1,1]
	v_rcp_f32_e32 v52, v52
	v_rcp_f32_e32 v53, v53
	v_rcp_f32_e32 v54, v54
	v_rcp_f32_e32 v55, v55
	v_pk_mul_f32 v[44:45], v[44:45], v[52:53]
	v_pk_mul_f32 v[46:47], v[46:47], v[54:55]
	v_pk_mul_f32 v[44:45], v[48:49], v[44:45]
	v_pk_mul_f32 v[46:47], v[50:51], v[46:47]
	v_mov_b64_e32 v[124:125], v[128:129]
	v_cvt_pk_bf16_f32 v126, v44, v45
	v_cvt_pk_bf16_f32 v127, v46, v47
	v_add_u32_e32 v58, 0x58000, v234
	global_store_dwordx4 v58, v[124:127], s[18:19]
	v_pk_fma_f32 v[44:45], v[180:181], v[8:9], v[188:189]
	v_pk_fma_f32 v[46:47], v[182:183], v[10:11], v[190:191]
	v_pk_fma_f32 v[48:49], v[172:173], v[4:5], v[168:169]
	v_pk_fma_f32 v[50:51], v[174:175], v[6:7], v[170:171]
	v_fmac_f32_dpp v44, v8, v192 row_shr:1 row_mask:0xf bank_mask:0xf
	v_fmac_f32_dpp v45, v9, v193 row_shr:1 row_mask:0xf bank_mask:0xf
	v_fmac_f32_dpp v46, v10, v194 row_shr:1 row_mask:0xf bank_mask:0xf
	v_fmac_f32_dpp v47, v11, v195 row_shr:1 row_mask:0xf bank_mask:0xf
	v_fmac_f32_dpp v48, v4, v176 row_shr:1 row_mask:0xf bank_mask:0xf
	v_fmac_f32_dpp v49, v5, v177 row_shr:1 row_mask:0xf bank_mask:0xf
	v_fmac_f32_dpp v50, v6, v178 row_shr:1 row_mask:0xf bank_mask:0xf
	v_fmac_f32_dpp v51, v7, v179 row_shr:1 row_mask:0xf bank_mask:0xf
	v_fmac_f32_dpp v44, v8, v236 row_shr:2 row_mask:0xf bank_mask:0xf
	v_fmac_f32_dpp v45, v9, v237 row_shr:2 row_mask:0xf bank_mask:0xf
	v_fmac_f32_dpp v46, v10, v238 row_shr:2 row_mask:0xf bank_mask:0xf
	v_fmac_f32_dpp v47, v11, v239 row_shr:2 row_mask:0xf bank_mask:0xf
	v_fmac_f32_dpp v48, v4, v184 row_shr:2 row_mask:0xf bank_mask:0xf
	v_fmac_f32_dpp v49, v5, v185 row_shr:2 row_mask:0xf bank_mask:0xf
	v_fmac_f32_dpp v50, v6, v186 row_shr:2 row_mask:0xf bank_mask:0xf
	v_fmac_f32_dpp v51, v7, v187 row_shr:2 row_mask:0xf bank_mask:0xf
	v_fmac_f32_dpp v44, v16, v28 row_ror:1 row_mask:0xf bank_mask:0xf
	v_fmac_f32_dpp v45, v17, v29 row_ror:1 row_mask:0xf bank_mask:0xf
	v_fmac_f32_dpp v46, v18, v30 row_ror:1 row_mask:0xf bank_mask:0xf
	v_fmac_f32_dpp v47, v19, v31 row_ror:1 row_mask:0xf bank_mask:0xf
	v_fmac_f32_dpp v48, v12, v36 row_ror:1 row_mask:0xf bank_mask:0xf
	v_fmac_f32_dpp v49, v13, v37 row_ror:1 row_mask:0xf bank_mask:0xf
	v_fmac_f32_dpp v50, v14, v38 row_ror:1 row_mask:0xf bank_mask:0xf
	v_fmac_f32_dpp v51, v15, v39 row_ror:1 row_mask:0xf bank_mask:0xf
	v_fmac_f32_dpp v44, v16, v32 row_ror:2 row_mask:0xf bank_mask:0xf
	v_fmac_f32_dpp v45, v17, v33 row_ror:2 row_mask:0xf bank_mask:0xf
	v_fmac_f32_dpp v46, v18, v34 row_ror:2 row_mask:0xf bank_mask:0xf
	v_fmac_f32_dpp v47, v19, v35 row_ror:2 row_mask:0xf bank_mask:0xf
	v_fmac_f32_dpp v48, v12, v40 row_ror:2 row_mask:0xf bank_mask:0xf
	v_fmac_f32_dpp v49, v13, v41 row_ror:2 row_mask:0xf bank_mask:0xf
	v_fmac_f32_dpp v50, v14, v42 row_ror:2 row_mask:0xf bank_mask:0xf
	v_fmac_f32_dpp v51, v15, v43 row_ror:2 row_mask:0xf bank_mask:0xf
	v_pk_mul_f32 v[52:53], v[44:45], v[240:241] op_sel_hi:[1,0]
	v_pk_mul_f32 v[54:55], v[46:47], v[240:241] op_sel_hi:[1,0]
	v_exp_f32_e32 v52, v52
	v_exp_f32_e32 v53, v53
	v_exp_f32_e32 v54, v54
	v_exp_f32_e32 v55, v55
	v_pk_add_f32 v[52:53], v[52:53], v[240:241] op_sel:[0,1] op_sel_hi:[1,1]
	v_pk_add_f32 v[54:55], v[54:55], v[240:241] op_sel:[0,1] op_sel_hi:[1,1]
	v_rcp_f32_e32 v52, v52
	v_rcp_f32_e32 v53, v53
	v_rcp_f32_e32 v54, v54
	v_rcp_f32_e32 v55, v55
	v_pk_mul_f32 v[44:45], v[44:45], v[52:53]
	v_pk_mul_f32 v[46:47], v[46:47], v[54:55]
	v_pk_mul_f32 v[44:45], v[48:49], v[44:45]
	v_pk_mul_f32 v[46:47], v[50:51], v[46:47]
	v_mov_b64_e32 v[88:89], v[130:131]
	v_cvt_pk_bf16_f32 v90, v44, v45
	v_cvt_pk_bf16_f32 v91, v46, v47
	v_add_u32_e32 v58, 0x84000, v234
	global_store_dwordx4 v58, v[88:91], s[18:19]
	s_cmp_eq_u32 s63, 0
	s_cbranch_scc1 .Leu_halo_skip_a1n1
	v_subrev_u32_e32 v58, 12, v56
	v_mul_u32_u24_e32 v58, 0xb000, v58
	v_lshl_add_u32 v58, v57, 5, v58
	s_mul_i32 s39, s12, 0x2c000
	s_lshl_b32 s40, s13, 9
	s_add_i32 s39, s39, s40
	s_lshl_b32 s40, s64, 2
	s_add_i32 s39, s39, s40
	s_add_u32 s20, s72, s39
	s_addc_u32 s21, s73, 0
	s_add_u32 s22, s20, 0x5800
	s_addc_u32 s23, s21, 0
	s_and_saveexec_b64 s[8:9], s[10:11]
	global_store_dwordx4 v58, v[8:11], s[20:21] offset:16
	global_store_dwordx4 v58, v[4:7], s[22:23] offset:16
	s_and_b32 s39, s12, 7
	s_cmp_lg_u32 s39, 7
	s_cbranch_scc1 .Leu_ffn_skip_a1n1
	v_subrev_u32_e32 v59, 14, v56
	v_mul_u32_u24_e32 v59, 0xb000, v59
	v_lshl_add_u32 v59, v57, 5, v59
	s_lshr_b32 s39, s12, 3
	s_mul_i32 s39, s39, 0x16000
	s_lshl_b32 s40, s13, 9
	s_add_i32 s39, s39, s40
	s_lshl_b32 s40, s64, 2
	s_add_i32 s39, s39, s40
	s_add_u32 s20, s28, s39
	s_addc_u32 s21, s29, 0
	s_add_u32 s22, s20, 0x5800
	s_addc_u32 s23, s21, 0
	global_store_dwordx4 v59, v[8:11], s[20:21] offset:16
	global_store_dwordx4 v59, v[4:7], s[22:23] offset:16
